# non-temporal cache policy on the once-read f32 weight loads of the conversion loops
# speedup vs baseline: 1.0071x; 1.0071x over previous
; #define LAS __attribute__((address_space(3)))
; DI void convert_mat(LAS float* tile, const float* src, int K, int N, bf16_t* dst, int ffn_in_mode, int wave_s) {
;   const int tid = tid_fresh(wave_s), tk = K >> 6, tn = N >> 6;
;   for (int t = blockIdx.x; t < tk * tn; t += gridDim.x) {
;     const int kb = t % tk, nb = t / tk;
; #pragma unroll
;     for (int i = 0; i < 2; ++i) {
;       const int r = (tid >> 4) + 32 * i, c = (tid & 15) * 4;
;       const f32x4 v = *(const f32x4*)(src + (size_t)(kb * 64 + r) * N + nb * 64 + c);
;       tile[r * 65 + c] = v[0]; tile[r * 65 + c + 1] = v[1]; tile[r * 65 + c + 2] = v[2]; tile[r * 65 + c + 3] = v[3];
; DI void convert_layer(LAS unsigned char* lds, const Params& p, int layer) {
;     ...
;   for (int i = 0; i < 2; ++i) {
;     convert_mat(tile, p.ffn_in + (size_t)(layer * 2 + i) * DM * 2 * DFF, DM, 2 * DFF, (bf16_t*)(p.ws + i * SZ_FFN_IN), 1, p.wave_s);
.LBB0_351:
	s_mov_b32 s18, 0x6dc9c883
	s_andn2_b64 vcc, exec, s[64:65]
	s_mov_b32 s19, 0x3fc45f30
	s_movk_i32 s20, 0x1800
	s_movk_i32 s21, 0x6000
	s_mov_b32 s22, 0x8000
	s_movk_i32 s23, 0xaff
	s_movk_i32 s24, 0x7fff
	s_movk_i32 s25, 0x1600
	s_cbranch_vccnz .LBB0_625
	s_cmp_lg_u32 s68, 0
	s_cselect_b64 s[4:5], -1, 0
	s_cmp_eq_u32 s68, 0
	s_cselect_b64 s[0:1], -1, 0
	s_and_b64 s[6:7], s[0:1], exec
	v_readlane_b32 s6, v254, 44
	v_readlane_b32 s7, v254, 45
	s_cselect_b32 s2, 0, 2
	s_andn2_b64 vcc, exec, s[6:7]
	v_cndmask_b32_e64 v0, 0, 1, s[6:7]
	v_cmp_ne_u32_e64 s[8:9], 1, v0
	v_mbcnt_lo_u32_b32 v4, -1, 0
	v_mbcnt_hi_u32_b32 v4, -1, v4
	s_cbranch_vccnz .LBB0_355
	v_readlane_b32 s36, v255, 29
	s_mul_i32 s6, s2, 0x1600000
	v_readlane_b32 s42, v255, 35
	v_readlane_b32 s43, v255, 36
	s_add_u32 s6, s42, s6
	v_lshlrev_b32_e32 v0, 4, v4
	s_addc_u32 s7, s43, 0
	v_or_b32_e32 v3, s79, v4
	v_and_b32_e32 v176, 0xf0, v0
	v_lshlrev_b32_e32 v4, 3, v4
	v_ashrrev_i32_e32 v2, 4, v3
	v_lshl_add_u64 v[0:1], s[6:7], 0, v[176:177]
	v_ashrrev_i32_e32 v3, 3, v3
	v_and_b32_e32 v6, 56, v4
	s_movk_i32 s6, 0x104
	v_add_u32_e32 v5, 0, v176
	v_lshl_add_u32 v7, v3, 2, 0
	v_mul_lo_u32 v4, v2, s6
	s_waitcnt vmcnt(0)
	v_mul_u32_u24_e32 v8, 0x104, v6
	v_add_u32_e32 v4, v5, v4
	v_add_u32_e32 v5, v7, v8
	v_lshlrev_b32_e32 v176, 1, v6
	s_mov_b32 s6, s73
	v_readlane_b32 s37, v255, 30
	v_readlane_b32 s38, v255, 31
	v_readlane_b32 s39, v255, 32
	v_readlane_b32 s40, v255, 33
	v_readlane_b32 s41, v255, 34
	v_readlane_b32 s44, v255, 37
	v_readlane_b32 s45, v255, 38
	v_readlane_b32 s46, v255, 39
	v_readlane_b32 s47, v255, 40
	v_readlane_b32 s48, v255, 41
	v_readlane_b32 s49, v255, 42
	v_readlane_b32 s50, v255, 43
	v_readlane_b32 s51, v255, 44
	s_ashr_i32 s7, s6, 31
	s_lshr_b32 s7, s7, 28
	s_add_i32 s7, s6, s7
	s_and_b32 s10, s7, 0x3fffff0
	s_lshl_b32 s7, s7, 2
	s_sub_i32 s11, s6, s10
	s_and_b32 s10, s7, 0xffffffc0
	s_lshl_b32 s12, s11, 6
	s_ashr_i32 s11, s10, 31
	v_lshl_add_u64 v[34:35], s[10:11], 2, v[0:1]
	v_add_u32_e32 v32, s12, v2
	v_mad_i64_i32 v[30:31], s[14:15], v32, s81, v[34:35]
	v_add_u32_e32 v36, 32, v32
	global_load_dwordx4 v[30:33], v[30:31], off nt
	v_mad_i64_i32 v[34:35], s[14:15], v36, s81, v[34:35]
	global_load_dwordx4 v[34:37], v[34:35], off nt
.LBB0_354:
	s_waitcnt vmcnt(0)
	v_mov_b32_e32 v6, v30
	v_mov_b32_e32 v7, v31
	v_mov_b32_e32 v8, v32
	v_mov_b32_e32 v9, v33
	v_mov_b32_e32 v10, v34
	v_mov_b32_e32 v11, v35
	v_mov_b32_e32 v12, v36
	v_mov_b32_e32 v13, v37
	v_add_u32_e32 v14, s10, v3
	v_cmp_lt_i32_e32 vcc, s23, v14
	v_and_b32_e32 v19, 0x7f, v14
	v_add_u32_e32 v16, 0x2080, v4
	v_cndmask_b32_e32 v15, 0, v213, vcc
	v_add_lshl_u32 v14, v15, v14, 1
	v_cndmask_b32_e32 v15, 0, v214, vcc
	v_and_b32_e32 v14, 0xffffff00, v14
	v_or3_b32 v14, v15, v19, v14
	v_add_u32_e32 v17, 0x2088, v4
	v_add_u32_e32 v18, 0x400, v5
	v_ashrrev_i32_e32 v15, 31, v14
	v_lshlrev_b64 v[14:15], 11, v[14:15]
	s_ashr_i32 s13, s12, 31
	v_lshl_add_u64 v[14:15], s[86:87], 0, v[14:15]
	v_lshl_add_u64 v[14:15], s[12:13], 1, v[14:15]
	v_lshl_add_u64 v[14:15], v[14:15], 0, v[176:177]
	s_load_dword s7, s[88:89], 0x10
	s_load_dword s12, s[88:89], 0x0
	s_waitcnt lgkmcnt(0)
	s_lshr_b32 s7, s7, 16
	s_cmp_lg_u32 s7, 0
	s_cselect_b64 s[10:11], -1, 0
	s_cmp_lg_u64 s[10:11], 0
	s_addc_u32 s6, s12, s6
	s_cmpk_lt_i32 s6, 0x580
	s_cselect_b64 s[100:101], -1, 0
	s_cbranch_scc0 .Lcv_skip_354
	s_ashr_i32 s7, s6, 31
	s_lshr_b32 s7, s7, 28
	s_add_i32 s7, s6, s7
	s_and_b32 s10, s7, 0x3fffff0
	s_lshl_b32 s7, s7, 2
	s_sub_i32 s11, s6, s10
	s_and_b32 s10, s7, 0xffffffc0
	s_lshl_b32 s12, s11, 6
	s_ashr_i32 s11, s10, 31
	v_lshl_add_u64 v[34:35], s[10:11], 2, v[0:1]
	v_add_u32_e32 v32, s12, v2
	v_mad_i64_i32 v[30:31], s[14:15], v32, s81, v[34:35]
	v_add_u32_e32 v36, 32, v32
	global_load_dwordx4 v[30:33], v[30:31], off nt
	v_mad_i64_i32 v[34:35], s[14:15], v36, s81, v[34:35]
	global_load_dwordx4 v[34:37], v[34:35], off nt

; #define LAS __attribute__((address_space(3)))
; DI void convert_mat(LAS float* tile, const float* src, int K, int N, bf16_t* dst, int ffn_in_mode, int wave_s) {
;   const int tid = tid_fresh(wave_s), tk = K >> 6, tn = N >> 6;
;   for (int t = blockIdx.x; t < tk * tn; t += gridDim.x) {
;     const int kb = t % tk, nb = t / tk;
; #pragma unroll
;     for (int i = 0; i < 2; ++i) {
;       const int r = (tid >> 4) + 32 * i, c = (tid & 15) * 4;
;       const f32x4 v = *(const f32x4*)(src + (size_t)(kb * 64 + r) * N + nb * 64 + c);
;       tile[r * 65 + c] = v[0]; tile[r * 65 + c + 1] = v[1]; tile[r * 65 + c + 2] = v[2]; tile[r * 65 + c + 3] = v[3];
; DI void convert_layer(LAS unsigned char* lds, const Params& p, int layer) {
;     ...
;     convert_mat(tile, p.ffn_out + (size_t)(layer * 2 + i) * DFF * DM, DFF, DM, (bf16_t*)(p.ws + OFF_FFN_OUT0 + i * SZ_FFN_OUT), 0, p.wave_s);
.LBB0_355:
	v_readlane_b32 s10, v254, 46
	v_readlane_b32 s11, v254, 47
	s_andn2_b64 vcc, exec, s[10:11]
	v_mbcnt_lo_u32_b32 v4, -1, 0
	v_mbcnt_hi_u32_b32 v4, -1, v4
	s_nop 0
	v_cndmask_b32_e64 v0, 0, 1, s[10:11]
	v_cmp_ne_u32_e64 s[6:7], 1, v0
	s_cbranch_vccnz .LBB0_358
	s_add_u32 s10, s86, 0x1600000
	v_readlane_b32 s36, v255, 29
	s_addc_u32 s11, s87, 0
	s_mul_i32 s12, s2, 0xb00000
	v_readlane_b32 s44, v255, 37
	v_readlane_b32 s45, v255, 38
	s_add_u32 s12, s44, s12
	v_lshlrev_b32_e32 v0, 4, v4
	s_addc_u32 s13, s45, 0
	v_or_b32_e32 v3, s79, v4
	v_and_b32_e32 v176, 0xf0, v0
	v_lshlrev_b32_e32 v4, 3, v4
	v_ashrrev_i32_e32 v2, 4, v3
	v_lshl_add_u64 v[0:1], s[12:13], 0, v[176:177]
	v_ashrrev_i32_e32 v3, 3, v3
	v_and_b32_e32 v6, 56, v4
	s_movk_i32 s12, 0x104
	v_add_u32_e32 v5, 0, v176
	v_lshl_add_u32 v7, v3, 2, 0
	v_mul_lo_u32 v4, v2, s12
	s_waitcnt vmcnt(0)
	v_mul_u32_u24_e32 v8, 0x104, v6
	v_add_u32_e32 v4, v5, v4
	v_add_u32_e32 v5, v7, v8
	v_lshlrev_b32_e32 v176, 1, v6
	s_mov_b32 s12, s73
	v_readlane_b32 s37, v255, 30
	v_readlane_b32 s38, v255, 31
	v_readlane_b32 s39, v255, 32
	v_readlane_b32 s40, v255, 33
	v_readlane_b32 s41, v255, 34
	v_readlane_b32 s42, v255, 35
	v_readlane_b32 s43, v255, 36
	v_readlane_b32 s46, v255, 39
	v_readlane_b32 s47, v255, 40
	v_readlane_b32 s48, v255, 41
	v_readlane_b32 s49, v255, 42
	v_readlane_b32 s50, v255, 43
	v_readlane_b32 s51, v255, 44
	s_mul_hi_i32 s13, s12, 0x2e8ba2e9
	s_lshr_b32 s14, s13, 31
	s_ashr_i32 s13, s13, 3
	s_add_i32 s13, s13, s14
	s_mul_i32 s15, s13, 44
	s_lshl_b32 s14, s13, 6
	s_sub_i32 s13, s12, s15
	s_lshl_b32 s16, s13, 6
	v_add_u32_e32 v30, s16, v2
	s_ashr_i32 s15, s14, 31
	v_ashrrev_i32_e32 v31, 31, v30
	v_lshl_add_u64 v[34:35], s[14:15], 2, v[0:1]
	v_add_u32_e32 v32, 32, v30
	v_lshlrev_b64 v[30:31], 12, v[30:31]
	v_ashrrev_i32_e32 v33, 31, v32
	v_lshl_add_u64 v[30:31], v[34:35], 0, v[30:31]
	v_lshlrev_b64 v[36:37], 12, v[32:33]
	global_load_dwordx4 v[30:33], v[30:31], off nt
	v_lshl_add_u64 v[34:35], v[34:35], 0, v[36:37]
	global_load_dwordx4 v[34:37], v[34:35], off nt
.LBB0_357:
	s_waitcnt vmcnt(0)
	v_mov_b32_e32 v6, v30
	v_mov_b32_e32 v7, v31
	v_mov_b32_e32 v8, v32
	v_mov_b32_e32 v9, v33
	v_mov_b32_e32 v10, v34
	v_mov_b32_e32 v11, v35
	v_mov_b32_e32 v12, v36
	v_mov_b32_e32 v13, v37
	v_add_u32_e32 v16, 0x2080, v4
	v_add_u32_e32 v17, 0x2088, v4
	v_add_u32_e32 v18, 0x400, v5
	v_mov_b64_e32 v[14:15], s[10:11]
	v_add_u32_e32 v19, s14, v3
	v_mad_i64_i32 v[14:15], s[14:15], v19, s25, v[14:15]
	s_ashr_i32 s17, s16, 31
	v_lshl_add_u64 v[14:15], s[16:17], 1, v[14:15]
	v_lshl_add_u64 v[14:15], v[14:15], 0, v[176:177]
	s_load_dword s13, s[88:89], 0x10
	s_load_dword s16, s[88:89], 0x0
	s_waitcnt lgkmcnt(0)
	s_lshr_b32 s13, s13, 16
	s_cmp_lg_u32 s13, 0
	s_cselect_b64 s[14:15], -1, 0
	s_cmp_lg_u64 s[14:15], 0
	s_addc_u32 s12, s16, s12
	s_cmpk_lt_i32 s12, 0x2c0
	s_cselect_b64 s[100:101], -1, 0
	s_cbranch_scc0 .Lcv_skip_357
	s_mul_hi_i32 s13, s12, 0x2e8ba2e9
	s_lshr_b32 s14, s13, 31
	s_ashr_i32 s13, s13, 3
	s_add_i32 s13, s13, s14
	s_mul_i32 s15, s13, 44
	s_lshl_b32 s14, s13, 6
	s_sub_i32 s13, s12, s15
	s_lshl_b32 s16, s13, 6
	v_add_u32_e32 v30, s16, v2
	s_ashr_i32 s15, s14, 31
	v_ashrrev_i32_e32 v31, 31, v30
	v_lshl_add_u64 v[34:35], s[14:15], 2, v[0:1]
	v_add_u32_e32 v32, 32, v30
	v_lshlrev_b64 v[30:31], 12, v[30:31]
	v_ashrrev_i32_e32 v33, 31, v32
	v_lshl_add_u64 v[30:31], v[34:35], 0, v[30:31]
	v_lshlrev_b64 v[36:37], 12, v[32:33]
	global_load_dwordx4 v[30:33], v[30:31], off nt
	v_lshl_add_u64 v[34:35], v[34:35], 0, v[36:37]
	global_load_dwordx4 v[34:37], v[34:35], off nt

; #define LAS __attribute__((address_space(3)))
; DI void convert_mat(LAS float* tile, const float* src, int K, int N, bf16_t* dst, int ffn_in_mode, int wave_s) {
;   const int tid = tid_fresh(wave_s), tk = K >> 6, tn = N >> 6;
;   for (int t = blockIdx.x; t < tk * tn; t += gridDim.x) {
;     const int kb = t % tk, nb = t / tk;
; #pragma unroll
;     for (int i = 0; i < 2; ++i) {
;       const int r = (tid >> 4) + 32 * i, c = (tid & 15) * 4;
;       const f32x4 v = *(const f32x4*)(src + (size_t)(kb * 64 + r) * N + nb * 64 + c);
;       tile[r * 65 + c] = v[0]; tile[r * 65 + c + 1] = v[1]; tile[r * 65 + c + 2] = v[2]; tile[r * 65 + c + 3] = v[3];
; DI void convert_layer(LAS unsigned char* lds, const Params& p, int layer) {
;     ...
;     convert_mat(tile, p.ffn_in + (size_t)(layer * 2 + i) * DM * 2 * DFF, DM, 2 * DFF, (bf16_t*)(p.ws + i * SZ_FFN_IN), 1, p.wave_s);
.LBB0_358:
	s_or_b32 s2, s2, 1
	s_and_b64 vcc, exec, s[8:9]
	v_mbcnt_lo_u32_b32 v4, -1, 0
	v_mbcnt_hi_u32_b32 v4, -1, v4
	s_cbranch_vccnz .LBB0_361
	s_add_u32 s8, s86, 0xb00000
	v_readlane_b32 s36, v255, 29
	s_addc_u32 s9, s87, 0
	s_mul_i32 s10, s2, 0x1600000
	v_readlane_b32 s42, v255, 35
	v_readlane_b32 s43, v255, 36
	s_add_u32 s10, s42, s10
	v_lshlrev_b32_e32 v0, 4, v4
	s_addc_u32 s11, s43, 0
	v_or_b32_e32 v3, s79, v4
	v_and_b32_e32 v176, 0xf0, v0
	v_lshlrev_b32_e32 v4, 3, v4
	v_ashrrev_i32_e32 v2, 4, v3
	v_lshl_add_u64 v[0:1], s[10:11], 0, v[176:177]
	v_ashrrev_i32_e32 v3, 3, v3
	v_and_b32_e32 v6, 56, v4
	s_movk_i32 s10, 0x104
	v_add_u32_e32 v5, 0, v176
	v_lshl_add_u32 v7, v3, 2, 0
	v_mul_lo_u32 v4, v2, s10
	s_waitcnt vmcnt(0)
	v_mul_u32_u24_e32 v8, 0x104, v6
	v_add_u32_e32 v4, v5, v4
	v_add_u32_e32 v5, v7, v8
	v_lshlrev_b32_e32 v176, 1, v6
	s_mov_b32 s10, s73
	v_readlane_b32 s37, v255, 30
	v_readlane_b32 s38, v255, 31
	v_readlane_b32 s39, v255, 32
	v_readlane_b32 s40, v255, 33
	v_readlane_b32 s41, v255, 34
	v_readlane_b32 s44, v255, 37
	v_readlane_b32 s45, v255, 38
	v_readlane_b32 s46, v255, 39
	v_readlane_b32 s47, v255, 40
	v_readlane_b32 s48, v255, 41
	v_readlane_b32 s49, v255, 42
	v_readlane_b32 s50, v255, 43
	v_readlane_b32 s51, v255, 44
	s_ashr_i32 s11, s10, 31
	s_lshr_b32 s11, s11, 28
	s_add_i32 s11, s10, s11
	s_and_b32 s12, s11, 0x3fffff0
	s_lshl_b32 s11, s11, 2
	s_sub_i32 s13, s10, s12
	s_and_b32 s12, s11, 0xffffffc0
	s_lshl_b32 s14, s13, 6
	s_ashr_i32 s13, s12, 31
	v_lshl_add_u64 v[34:35], s[12:13], 2, v[0:1]
	v_add_u32_e32 v32, s14, v2
	v_mad_i64_i32 v[30:31], s[16:17], v32, s81, v[34:35]
	v_add_u32_e32 v36, 32, v32
	global_load_dwordx4 v[30:33], v[30:31], off nt
	v_mad_i64_i32 v[34:35], s[16:17], v36, s81, v[34:35]
	global_load_dwordx4 v[34:37], v[34:35], off nt
.LBB0_360:
	s_waitcnt vmcnt(0)
	v_mov_b32_e32 v6, v30
	v_mov_b32_e32 v7, v31
	v_mov_b32_e32 v8, v32
	v_mov_b32_e32 v9, v33
	v_mov_b32_e32 v10, v34
	v_mov_b32_e32 v11, v35
	v_mov_b32_e32 v12, v36
	v_mov_b32_e32 v13, v37
	v_add_u32_e32 v14, s12, v3
	v_cmp_lt_i32_e32 vcc, s23, v14
	v_and_b32_e32 v19, 0x7f, v14
	v_add_u32_e32 v16, 0x2080, v4
	v_cndmask_b32_e32 v15, 0, v213, vcc
	v_add_lshl_u32 v14, v15, v14, 1
	v_cndmask_b32_e32 v15, 0, v214, vcc
	v_and_b32_e32 v14, 0xffffff00, v14
	v_or3_b32 v14, v15, v19, v14
	v_add_u32_e32 v17, 0x2088, v4
	v_add_u32_e32 v18, 0x400, v5
	v_ashrrev_i32_e32 v15, 31, v14
	v_lshlrev_b64 v[14:15], 11, v[14:15]
	s_ashr_i32 s15, s14, 31
	v_lshl_add_u64 v[14:15], s[8:9], 0, v[14:15]
	v_lshl_add_u64 v[14:15], s[14:15], 1, v[14:15]
	v_lshl_add_u64 v[14:15], v[14:15], 0, v[176:177]
	s_load_dword s11, s[88:89], 0x10
	s_load_dword s14, s[88:89], 0x0
	s_waitcnt lgkmcnt(0)
	s_lshr_b32 s11, s11, 16
	s_cmp_lg_u32 s11, 0
	s_cselect_b64 s[12:13], -1, 0
	s_cmp_lg_u64 s[12:13], 0
	s_addc_u32 s10, s14, s10
	s_cmpk_lt_i32 s10, 0x580
	s_cselect_b64 s[100:101], -1, 0
	s_cbranch_scc0 .Lcv_skip_360
	s_ashr_i32 s11, s10, 31
	s_lshr_b32 s11, s11, 28
	s_add_i32 s11, s10, s11
	s_and_b32 s12, s11, 0x3fffff0
	s_lshl_b32 s11, s11, 2
	s_sub_i32 s13, s10, s12
	s_and_b32 s12, s11, 0xffffffc0
	s_lshl_b32 s14, s13, 6
	s_ashr_i32 s13, s12, 31
	v_lshl_add_u64 v[34:35], s[12:13], 2, v[0:1]
	v_add_u32_e32 v32, s14, v2
	v_mad_i64_i32 v[30:31], s[16:17], v32, s81, v[34:35]
	v_add_u32_e32 v36, 32, v32
	global_load_dwordx4 v[30:33], v[30:31], off nt
	v_mad_i64_i32 v[34:35], s[16:17], v36, s81, v[34:35]
	global_load_dwordx4 v[34:37], v[34:35], off nt

; #define LAS __attribute__((address_space(3)))
; DI void convert_mat(LAS float* tile, const float* src, int K, int N, bf16_t* dst, int ffn_in_mode, int wave_s) {
;   const int tid = tid_fresh(wave_s), tk = K >> 6, tn = N >> 6;
;   for (int t = blockIdx.x; t < tk * tn; t += gridDim.x) {
;     const int kb = t % tk, nb = t / tk;
; #pragma unroll
;     for (int i = 0; i < 2; ++i) {
;       const int r = (tid >> 4) + 32 * i, c = (tid & 15) * 4;
;       const f32x4 v = *(const f32x4*)(src + (size_t)(kb * 64 + r) * N + nb * 64 + c);
;       tile[r * 65 + c] = v[0]; tile[r * 65 + c + 1] = v[1]; tile[r * 65 + c + 2] = v[2]; tile[r * 65 + c + 3] = v[3];
; DI void convert_layer(LAS unsigned char* lds, const Params& p, int layer) {
;     ...
;     convert_mat(tile, p.ffn_out + (size_t)(layer * 2 + i) * DFF * DM, DFF, DM, (bf16_t*)(p.ws + OFF_FFN_OUT0 + i * SZ_FFN_OUT), 0, p.wave_s);
.LBB0_361:
	s_and_b64 vcc, exec, s[6:7]
	v_mbcnt_lo_u32_b32 v4, -1, 0
	v_mbcnt_hi_u32_b32 v4, -1, v4
	s_cbranch_vccnz .LBB0_364
	s_add_u32 s6, s86, 0x1b80000
	v_readlane_b32 s36, v255, 29
	s_addc_u32 s7, s87, 0
	s_mul_i32 s2, s2, 0xb00000
	v_readlane_b32 s44, v255, 37
	v_or_b32_e32 v3, s79, v4
	v_lshlrev_b32_e32 v0, 4, v4
	v_lshlrev_b32_e32 v4, 3, v4
	v_readlane_b32 s45, v255, 38
	s_add_u32 s8, s44, s2
	v_ashrrev_i32_e32 v2, 4, v3
	v_and_b32_e32 v176, 0xf0, v0
	v_ashrrev_i32_e32 v3, 3, v3
	v_and_b32_e32 v6, 56, v4
	s_movk_i32 s2, 0x104
	s_addc_u32 s9, s45, 0
	v_add_u32_e32 v5, 0, v176
	v_lshl_add_u32 v7, v3, 2, 0
	v_mul_lo_u32 v4, v2, s2
	s_waitcnt vmcnt(0)
	v_mul_u32_u24_e32 v8, 0x104, v6
	v_lshl_add_u64 v[0:1], s[8:9], 0, v[176:177]
	v_add_u32_e32 v4, v5, v4
	v_add_u32_e32 v5, v7, v8
	v_lshlrev_b32_e32 v176, 1, v6
	s_mov_b32 s2, s73
	v_readlane_b32 s37, v255, 30
	v_readlane_b32 s38, v255, 31
	v_readlane_b32 s39, v255, 32
	v_readlane_b32 s40, v255, 33
	v_readlane_b32 s41, v255, 34
	v_readlane_b32 s42, v255, 35
	v_readlane_b32 s43, v255, 36
	v_readlane_b32 s46, v255, 39
	v_readlane_b32 s47, v255, 40
	v_readlane_b32 s48, v255, 41
	v_readlane_b32 s49, v255, 42
	v_readlane_b32 s50, v255, 43
	v_readlane_b32 s51, v255, 44
	s_mul_hi_i32 s8, s2, 0x2e8ba2e9
	s_lshr_b32 s9, s8, 31
	s_ashr_i32 s8, s8, 3
	s_add_i32 s8, s8, s9
	s_mul_i32 s9, s8, 44
	s_sub_i32 s10, s2, s9
	s_lshl_b32 s10, s10, 6
	s_lshl_b32 s8, s8, 6
	v_add_u32_e32 v30, s10, v2
	s_ashr_i32 s9, s8, 31
	v_ashrrev_i32_e32 v31, 31, v30
	v_lshl_add_u64 v[34:35], s[8:9], 2, v[0:1]
	v_add_u32_e32 v32, 32, v30
	v_lshlrev_b64 v[30:31], 12, v[30:31]
	v_ashrrev_i32_e32 v33, 31, v32
	v_lshl_add_u64 v[30:31], v[34:35], 0, v[30:31]
	v_lshlrev_b64 v[36:37], 12, v[32:33]
	global_load_dwordx4 v[30:33], v[30:31], off nt
	v_lshl_add_u64 v[34:35], v[34:35], 0, v[36:37]
	global_load_dwordx4 v[34:37], v[34:35], off nt
.LBB0_363:
	s_waitcnt vmcnt(0)
	v_mov_b32_e32 v6, v30
	v_mov_b32_e32 v7, v31
	v_mov_b32_e32 v8, v32
	v_mov_b32_e32 v9, v33
	v_mov_b32_e32 v10, v34
	v_mov_b32_e32 v11, v35
	v_mov_b32_e32 v12, v36
	v_mov_b32_e32 v13, v37
	v_add_u32_e32 v16, 0x2080, v4
	v_add_u32_e32 v17, 0x2088, v4
	v_add_u32_e32 v18, 0x400, v5
	v_mov_b64_e32 v[14:15], s[6:7]
	v_add_u32_e32 v19, s8, v3
	v_mad_i64_i32 v[14:15], s[8:9], v19, s25, v[14:15]
	s_ashr_i32 s11, s10, 31
	v_lshl_add_u64 v[14:15], s[10:11], 1, v[14:15]
	v_lshl_add_u64 v[14:15], v[14:15], 0, v[176:177]
	s_load_dword s8, s[88:89], 0x10
	s_load_dword s10, s[88:89], 0x0
	s_waitcnt lgkmcnt(0)
	s_lshr_b32 s8, s8, 16
	s_cmp_lg_u32 s8, 0
	s_cselect_b64 s[8:9], -1, 0
	s_cmp_lg_u64 s[8:9], 0
	s_addc_u32 s2, s10, s2
	s_cmpk_lt_i32 s2, 0x2c0
	s_cselect_b64 s[100:101], -1, 0
	s_cbranch_scc0 .Lcv_skip_363
	s_mul_hi_i32 s8, s2, 0x2e8ba2e9
	s_lshr_b32 s9, s8, 31
	s_ashr_i32 s8, s8, 3
	s_add_i32 s8, s8, s9
	s_mul_i32 s9, s8, 44
	s_sub_i32 s10, s2, s9
	s_lshl_b32 s10, s10, 6
	s_lshl_b32 s8, s8, 6
	v_add_u32_e32 v30, s10, v2
	s_ashr_i32 s9, s8, 31
	v_ashrrev_i32_e32 v31, 31, v30
	v_lshl_add_u64 v[34:35], s[8:9], 2, v[0:1]
	v_add_u32_e32 v32, 32, v30
	v_lshlrev_b64 v[30:31], 12, v[30:31]
	v_ashrrev_i32_e32 v33, 31, v32
	v_lshl_add_u64 v[30:31], v[34:35], 0, v[30:31]
	v_lshlrev_b64 v[36:37], 12, v[32:33]
	global_load_dwordx4 v[30:33], v[30:31], off nt
	v_lshl_add_u64 v[34:35], v[34:35], 0, v[36:37]
	global_load_dwordx4 v[34:37], v[34:35], off nt

; #define LAS __attribute__((address_space(3)))
; DI void convert_mat(LAS float* tile, const float* src, int K, int N, bf16_t* dst, int ffn_in_mode, int wave_s) {
;   const int tid = tid_fresh(wave_s), tk = K >> 6, tn = N >> 6;
;   for (int t = blockIdx.x; t < tk * tn; t += gridDim.x) {
;     const int kb = t % tk, nb = t / tk;
; #pragma unroll
;     for (int i = 0; i < 2; ++i) {
;       const int r = (tid >> 4) + 32 * i, c = (tid & 15) * 4;
;       const f32x4 v = *(const f32x4*)(src + (size_t)(kb * 64 + r) * N + nb * 64 + c);
;       tile[r * 65 + c] = v[0]; tile[r * 65 + c + 1] = v[1]; tile[r * 65 + c + 2] = v[2]; tile[r * 65 + c + 3] = v[3];
; DI void convert_layer(LAS unsigned char* lds, const Params& p, int layer) {
;     ...
;   if (layer == 0) {
;     convert_mat(tile, p.wqkv, DM, 1536, (bf16_t*)(p.ws + OFF_MIX_IN), 0, p.wave_s);
;     convert_mat(tile, p.wao, DM, DM, (bf16_t*)(p.ws + OFF_MIX_OUT), 0, p.wave_s);
;   } else {
;     convert_mat(tile, p.wret_in, DM, 6144, (bf16_t*)(p.ws + OFF_MIX_IN), 0, p.wave_s);
.LBB0_364:
	s_add_u32 s6, s86, 0x2100000
	s_addc_u32 s7, s87, 0
	s_mov_b64 s[8:9], -1
	s_and_b64 vcc, exec, s[4:5]
	s_cbranch_vccz .LBB0_372
	v_readlane_b32 s4, v254, 48
	v_readlane_b32 s5, v254, 49
	s_andn2_b64 vcc, exec, s[4:5]
	v_mbcnt_lo_u32_b32 v4, -1, 0
	v_mbcnt_hi_u32_b32 v4, -1, v4
	s_cbranch_vccnz .LBB0_368
	v_or_b32_e32 v3, s79, v4
	v_lshlrev_b32_e32 v0, 4, v4
	v_lshlrev_b32_e32 v4, 3, v4
	v_ashrrev_i32_e32 v2, 4, v3
	v_and_b32_e32 v176, 0xf0, v0
	v_ashrrev_i32_e32 v3, 3, v3
	v_and_b32_e32 v6, 56, v4
	s_movk_i32 s2, 0x104
	v_add_u32_e32 v5, 0, v176
	v_lshl_add_u32 v7, v3, 2, 0
	v_mul_lo_u32 v4, v2, s2
	s_waitcnt vmcnt(0)
	v_mul_u32_u24_e32 v8, 0x104, v6
	v_lshl_add_u64 v[0:1], s[60:61], 0, v[176:177]
	v_add_u32_e32 v4, v5, v4
	v_add_u32_e32 v5, v7, v8
	v_lshlrev_b32_e32 v176, 1, v6
	s_mov_b32 s2, s73
	s_ashr_i32 s4, s2, 31
	s_lshr_b32 s4, s4, 28
	s_add_i32 s4, s2, s4
	s_and_b32 s5, s4, 0x3fffff0
	s_lshl_b32 s4, s4, 2
	s_sub_i32 s5, s2, s5
	s_andn2_b32 s4, s4, 63
	s_lshl_b32 s8, s5, 6
	s_ashr_i32 s5, s4, 31
	v_lshl_add_u64 v[34:35], s[4:5], 2, v[0:1]
	v_add_u32_e32 v32, s8, v2
	v_mad_i64_i32 v[30:31], s[10:11], v32, s21, v[34:35]
	v_add_u32_e32 v36, 32, v32
	global_load_dwordx4 v[30:33], v[30:31], off nt
	v_mad_i64_i32 v[34:35], s[10:11], v36, s21, v[34:35]
	global_load_dwordx4 v[34:37], v[34:35], off nt
.LBB0_367:
	s_waitcnt vmcnt(0)
	v_mov_b32_e32 v6, v30
	v_mov_b32_e32 v7, v31
	v_mov_b32_e32 v8, v32
	v_mov_b32_e32 v9, v33
	v_mov_b32_e32 v10, v34
	v_mov_b32_e32 v11, v35
	v_mov_b32_e32 v12, v36
	v_mov_b32_e32 v13, v37
	v_add_u32_e32 v14, s4, v3
	v_add_u32_e32 v16, 0x2080, v4
	v_add_u32_e32 v17, 0x2088, v4
	v_add_u32_e32 v18, 0x400, v5
	v_ashrrev_i32_e32 v15, 31, v14
	v_lshlrev_b64 v[14:15], 11, v[14:15]
	s_ashr_i32 s9, s8, 31
	v_lshl_add_u64 v[14:15], s[6:7], 0, v[14:15]
	v_lshl_add_u64 v[14:15], s[8:9], 1, v[14:15]
	v_lshl_add_u64 v[14:15], v[14:15], 0, v[176:177]
	s_load_dword s4, s[88:89], 0x10
	s_load_dword s8, s[88:89], 0x0
	s_waitcnt lgkmcnt(0)
	s_lshr_b32 s4, s4, 16
	s_cmp_lg_u32 s4, 0
	s_cselect_b64 s[4:5], -1, 0
	s_cmp_lg_u64 s[4:5], 0
	s_addc_u32 s2, s8, s2
	s_cmpk_lt_i32 s2, 0x600
	s_cselect_b64 s[100:101], -1, 0
	s_cbranch_scc0 .Lcv_skip_367
	s_ashr_i32 s4, s2, 31
	s_lshr_b32 s4, s4, 28
	s_add_i32 s4, s2, s4
	s_and_b32 s5, s4, 0x3fffff0
	s_lshl_b32 s4, s4, 2
	s_sub_i32 s5, s2, s5
	s_andn2_b32 s4, s4, 63
	s_lshl_b32 s8, s5, 6
	s_ashr_i32 s5, s4, 31
	v_lshl_add_u64 v[34:35], s[4:5], 2, v[0:1]
	v_add_u32_e32 v32, s8, v2
	v_mad_i64_i32 v[30:31], s[10:11], v32, s21, v[34:35]
	v_add_u32_e32 v36, 32, v32
	global_load_dwordx4 v[30:33], v[30:31], off nt
	v_mad_i64_i32 v[34:35], s[10:11], v36, s21, v[34:35]
	global_load_dwordx4 v[34:37], v[34:35], off nt

; DI void convert_mat(LAS float* tile, const float* src, int K, int N, bf16_t* dst, int ffn_in_mode, int wave_s) {
;   const int tid = tid_fresh(wave_s), tk = K >> 6, tn = N >> 6;
;   for (int t = blockIdx.x; t < tk * tn; t += gridDim.x) {
;     const int kb = t % tk, nb = t / tk;
; #pragma unroll
;     for (int i = 0; i < 2; ++i) {
;       const int r = (tid >> 4) + 32 * i, c = (tid & 15) * 4;
;       const f32x4 v = *(const f32x4*)(src + (size_t)(kb * 64 + r) * N + nb * 64 + c);
;       tile[r * 65 + c] = v[0]; tile[r * 65 + c + 1] = v[1]; tile[r * 65 + c + 2] = v[2]; tile[r * 65 + c + 3] = v[3];
;     }
; DI void convert_layer(LAS unsigned char* lds, const Params& p, int layer) {
;     ...
;     convert_mat(tile, p.wret_o, 2048, DM, (bf16_t*)(p.ws + OFF_MIX_OUT), 0, p.wave_s);
.LBB0_368:
	v_readlane_b32 s4, v254, 2
	v_readlane_b32 s5, v254, 3
	s_andn2_b64 vcc, exec, s[4:5]
	v_mbcnt_lo_u32_b32 v4, -1, 0
	v_mbcnt_hi_u32_b32 v4, -1, v4
	s_cbranch_vccnz .LBB0_371
	v_or_b32_e32 v3, s79, v4
	v_lshlrev_b32_e32 v0, 4, v4
	v_lshlrev_b32_e32 v4, 3, v4
	v_ashrrev_i32_e32 v2, 4, v3
	v_and_b32_e32 v176, 0xf0, v0
	v_ashrrev_i32_e32 v3, 3, v3
	v_and_b32_e32 v6, 56, v4
	s_movk_i32 s2, 0x104
	s_add_u32 s4, s86, 0x2d00000
	v_add_u32_e32 v5, 0, v176
	v_lshl_add_u32 v7, v3, 2, 0
	v_mul_lo_u32 v4, v2, s2
	s_waitcnt vmcnt(0)
	v_mul_u32_u24_e32 v8, 0x104, v6
	s_addc_u32 s5, s87, 0
	v_lshl_add_u64 v[0:1], s[62:63], 0, v[176:177]
	v_add_u32_e32 v4, v5, v4
	v_add_u32_e32 v5, v7, v8
	v_lshlrev_b32_e32 v176, 1, v6
	s_mov_b32 s2, s73
	s_ashr_i32 s8, s2, 31
	s_lshr_b32 s8, s8, 27
	s_add_i32 s8, s2, s8
	s_and_b32 s9, s8, 0x3ffffe0
	s_sub_i32 s9, s2, s9
	s_lshl_b32 s8, s8, 1
	s_lshl_b32 s10, s9, 6
	s_andn2_b32 s8, s8, 63
	v_add_u32_e32 v30, s10, v2
	s_ashr_i32 s9, s8, 31
	v_ashrrev_i32_e32 v31, 31, v30
	v_lshl_add_u64 v[34:35], s[8:9], 2, v[0:1]
	v_add_u32_e32 v32, 32, v30
	v_lshlrev_b64 v[30:31], 12, v[30:31]
	v_ashrrev_i32_e32 v33, 31, v32
	v_lshl_add_u64 v[30:31], v[34:35], 0, v[30:31]
	v_lshlrev_b64 v[36:37], 12, v[32:33]
	global_load_dwordx4 v[30:33], v[30:31], off nt
	v_lshl_add_u64 v[34:35], v[34:35], 0, v[36:37]
	global_load_dwordx4 v[34:37], v[34:35], off nt
.LBB0_370:
	s_waitcnt vmcnt(0)
	v_mov_b32_e32 v6, v30
	v_mov_b32_e32 v7, v31
	v_mov_b32_e32 v8, v32
	v_mov_b32_e32 v9, v33
	v_mov_b32_e32 v10, v34
	v_mov_b32_e32 v11, v35
	v_mov_b32_e32 v12, v36
	v_mov_b32_e32 v13, v37
	v_add_u32_e32 v14, s8, v3
	v_add_u32_e32 v16, 0x2080, v4
	v_add_u32_e32 v17, 0x2088, v4
	v_add_u32_e32 v18, 0x400, v5
	v_ashrrev_i32_e32 v15, 31, v14
	v_lshlrev_b64 v[14:15], 12, v[14:15]
	s_ashr_i32 s11, s10, 31
	v_lshl_add_u64 v[14:15], s[4:5], 0, v[14:15]
	v_lshl_add_u64 v[14:15], s[10:11], 1, v[14:15]
	v_lshl_add_u64 v[14:15], v[14:15], 0, v[176:177]
	s_load_dword s8, s[88:89], 0x10
	s_load_dword s10, s[88:89], 0x0
	s_waitcnt lgkmcnt(0)
	s_lshr_b32 s8, s8, 16
	s_cmp_lg_u32 s8, 0
	s_cselect_b64 s[8:9], -1, 0
	s_cmp_lg_u64 s[8:9], 0
	s_addc_u32 s2, s10, s2
	s_cmpk_lt_i32 s2, 0x200
	s_cselect_b64 s[100:101], -1, 0
	s_cbranch_scc0 .Lcv_skip_370
	s_ashr_i32 s8, s2, 31
	s_lshr_b32 s8, s8, 27
	s_add_i32 s8, s2, s8
	s_and_b32 s9, s8, 0x3ffffe0
	s_sub_i32 s9, s2, s9
	s_lshl_b32 s8, s8, 1
	s_lshl_b32 s10, s9, 6
	s_andn2_b32 s8, s8, 63
	v_add_u32_e32 v30, s10, v2
	s_ashr_i32 s9, s8, 31
	v_ashrrev_i32_e32 v31, 31, v30
	v_lshl_add_u64 v[34:35], s[8:9], 2, v[0:1]
	v_add_u32_e32 v32, 32, v30
	v_lshlrev_b64 v[30:31], 12, v[30:31]
	v_ashrrev_i32_e32 v33, 31, v32
	v_lshl_add_u64 v[30:31], v[34:35], 0, v[30:31]
	v_lshlrev_b64 v[36:37], 12, v[32:33]
	global_load_dwordx4 v[30:33], v[30:31], off nt
	v_lshl_add_u64 v[34:35], v[34:35], 0, v[36:37]
	global_load_dwordx4 v[34:37], v[34:35], off nt

; DI void convert_mat(LAS float* tile, const float* src, int K, int N, bf16_t* dst, int ffn_in_mode, int wave_s) {
;   const int tid = tid_fresh(wave_s), tk = K >> 6, tn = N >> 6;
;   for (int t = blockIdx.x; t < tk * tn; t += gridDim.x) {
;     const int kb = t % tk, nb = t / tk;
; #pragma unroll
;     for (int i = 0; i < 2; ++i) {
;       const int r = (tid >> 4) + 32 * i, c = (tid & 15) * 4;
;       const f32x4 v = *(const f32x4*)(src + (size_t)(kb * 64 + r) * N + nb * 64 + c);
;       tile[r * 65 + c] = v[0]; tile[r * 65 + c + 1] = v[1]; tile[r * 65 + c + 2] = v[2]; tile[r * 65 + c + 3] = v[3];
;     }
; DI void convert_layer(LAS unsigned char* lds, const Params& p, int layer) {
;     ...
;     convert_mat(tile, p.wqkv, DM, 1536, (bf16_t*)(p.ws + OFF_MIX_IN), 0, p.wave_s);
.LBB0_372:
	s_and_b64 vcc, exec, s[8:9]
	s_cbranch_vccz .LBB0_379
	v_readlane_b32 s4, v254, 50
	v_readlane_b32 s5, v254, 51
	s_andn2_b64 vcc, exec, s[4:5]
	v_mbcnt_lo_u32_b32 v4, -1, 0
	v_mbcnt_hi_u32_b32 v4, -1, v4
	s_cbranch_vccnz .LBB0_376
	v_or_b32_e32 v3, s79, v4
	v_lshlrev_b32_e32 v0, 4, v4
	v_lshlrev_b32_e32 v4, 3, v4
	v_ashrrev_i32_e32 v2, 4, v3
	v_and_b32_e32 v176, 0xf0, v0
	v_readlane_b32 s36, v255, 29
	v_ashrrev_i32_e32 v3, 3, v3
	v_and_b32_e32 v6, 56, v4
	s_movk_i32 s2, 0x104
	v_readlane_b32 s46, v255, 39
	v_readlane_b32 s47, v255, 40
	v_add_u32_e32 v5, 0, v176
	v_lshl_add_u32 v7, v3, 2, 0
	v_mul_lo_u32 v4, v2, s2
	s_waitcnt vmcnt(0)
	v_mul_u32_u24_e32 v8, 0x104, v6
	v_lshl_add_u64 v[0:1], s[46:47], 0, v[176:177]
	v_add_u32_e32 v4, v5, v4
	v_add_u32_e32 v5, v7, v8
	v_lshlrev_b32_e32 v176, 1, v6
	s_mov_b32 s2, s73
	v_readlane_b32 s37, v255, 30
	v_readlane_b32 s38, v255, 31
	v_readlane_b32 s39, v255, 32
	v_readlane_b32 s40, v255, 33
	v_readlane_b32 s41, v255, 34
	v_readlane_b32 s42, v255, 35
	v_readlane_b32 s43, v255, 36
	v_readlane_b32 s44, v255, 37
	v_readlane_b32 s45, v255, 38
	v_readlane_b32 s48, v255, 41
	v_readlane_b32 s49, v255, 42
	v_readlane_b32 s50, v255, 43
	v_readlane_b32 s51, v255, 44
	s_ashr_i32 s4, s2, 31
	s_lshr_b32 s4, s4, 28
	s_add_i32 s4, s2, s4
	s_and_b32 s5, s4, 0x3fffff0
	s_lshl_b32 s4, s4, 2
	s_sub_i32 s5, s2, s5
	s_andn2_b32 s4, s4, 63
	s_lshl_b32 s8, s5, 6
	s_ashr_i32 s5, s4, 31
	v_lshl_add_u64 v[34:35], s[4:5], 2, v[0:1]
	v_add_u32_e32 v32, s8, v2
	v_mad_i64_i32 v[30:31], s[10:11], v32, s20, v[34:35]
	v_add_u32_e32 v36, 32, v32
	global_load_dwordx4 v[30:33], v[30:31], off nt
	v_mad_i64_i32 v[34:35], s[10:11], v36, s20, v[34:35]
	global_load_dwordx4 v[34:37], v[34:35], off nt
.LBB0_375:
	s_waitcnt vmcnt(0)
	v_mov_b32_e32 v6, v30
	v_mov_b32_e32 v7, v31
	v_mov_b32_e32 v8, v32
	v_mov_b32_e32 v9, v33
	v_mov_b32_e32 v10, v34
	v_mov_b32_e32 v11, v35
	v_mov_b32_e32 v12, v36
	v_mov_b32_e32 v13, v37
	v_add_u32_e32 v14, s4, v3
	v_add_u32_e32 v16, 0x2080, v4
	v_add_u32_e32 v17, 0x2088, v4
	v_add_u32_e32 v18, 0x400, v5
	v_ashrrev_i32_e32 v15, 31, v14
	v_lshlrev_b64 v[14:15], 11, v[14:15]
	s_ashr_i32 s9, s8, 31
	v_lshl_add_u64 v[14:15], s[6:7], 0, v[14:15]
	v_lshl_add_u64 v[14:15], s[8:9], 1, v[14:15]
	v_lshl_add_u64 v[14:15], v[14:15], 0, v[176:177]
	s_load_dword s4, s[88:89], 0x10
	s_load_dword s8, s[88:89], 0x0
	s_waitcnt lgkmcnt(0)
	s_lshr_b32 s4, s4, 16
	s_cmp_lg_u32 s4, 0
	s_cselect_b64 s[4:5], -1, 0
	s_cmp_lg_u64 s[4:5], 0
	s_addc_u32 s2, s8, s2
	s_cmpk_lt_i32 s2, 0x180
	s_cselect_b64 s[100:101], -1, 0
	s_cbranch_scc0 .Lcv_skip_375
	s_ashr_i32 s4, s2, 31
	s_lshr_b32 s4, s4, 28
	s_add_i32 s4, s2, s4
	s_and_b32 s5, s4, 0x3fffff0
	s_lshl_b32 s4, s4, 2
	s_sub_i32 s5, s2, s5
	s_andn2_b32 s4, s4, 63
	s_lshl_b32 s8, s5, 6
	s_ashr_i32 s5, s4, 31
	v_lshl_add_u64 v[34:35], s[4:5], 2, v[0:1]
	v_add_u32_e32 v32, s8, v2
	v_mad_i64_i32 v[30:31], s[10:11], v32, s20, v[34:35]
	v_add_u32_e32 v36, 32, v32
	global_load_dwordx4 v[30:33], v[30:31], off nt
	v_mad_i64_i32 v[34:35], s[10:11], v36, s20, v[34:35]
	global_load_dwordx4 v[34:37], v[34:35], off nt

; DI void convert_mat(LAS float* tile, const float* src, int K, int N, bf16_t* dst, int ffn_in_mode, int wave_s) {
;   const int tid = tid_fresh(wave_s), tk = K >> 6, tn = N >> 6;
;   for (int t = blockIdx.x; t < tk * tn; t += gridDim.x) {
;     const int kb = t % tk, nb = t / tk;
; #pragma unroll
;     for (int i = 0; i < 2; ++i) {
;       const int r = (tid >> 4) + 32 * i, c = (tid & 15) * 4;
;       const f32x4 v = *(const f32x4*)(src + (size_t)(kb * 64 + r) * N + nb * 64 + c);
;       tile[r * 65 + c] = v[0]; tile[r * 65 + c + 1] = v[1]; tile[r * 65 + c + 2] = v[2]; tile[r * 65 + c + 3] = v[3];
;     }
; DI void convert_layer(LAS unsigned char* lds, const Params& p, int layer) {
;     ...
;     convert_mat(tile, p.wao, DM, DM, (bf16_t*)(p.ws + OFF_MIX_OUT), 0, p.wave_s);
.LBB0_376:
	v_readlane_b32 s4, v254, 6
	v_readlane_b32 s5, v254, 7
	s_andn2_b64 vcc, exec, s[4:5]
	v_mbcnt_lo_u32_b32 v4, -1, 0
	v_mbcnt_hi_u32_b32 v4, -1, v4
	s_cbranch_vccnz .LBB0_379
	v_or_b32_e32 v3, s79, v4
	v_lshlrev_b32_e32 v0, 4, v4
	v_lshlrev_b32_e32 v4, 3, v4
	v_ashrrev_i32_e32 v2, 4, v3
	v_and_b32_e32 v176, 0xf0, v0
	v_readlane_b32 s36, v255, 29
	v_ashrrev_i32_e32 v3, 3, v3
	v_and_b32_e32 v6, 56, v4
	s_movk_i32 s2, 0x104
	s_add_u32 s4, s86, 0x2d00000
	v_readlane_b32 s48, v255, 41
	v_readlane_b32 s49, v255, 42
	v_add_u32_e32 v5, 0, v176
	v_lshl_add_u32 v7, v3, 2, 0
	v_mul_lo_u32 v4, v2, s2
	s_waitcnt vmcnt(0)
	v_mul_u32_u24_e32 v8, 0x104, v6
	s_addc_u32 s5, s87, 0
	v_lshl_add_u64 v[0:1], s[48:49], 0, v[176:177]
	v_add_u32_e32 v4, v5, v4
	v_add_u32_e32 v5, v7, v8
	v_lshlrev_b32_e32 v176, 1, v6
	s_mov_b32 s2, s73
	v_readlane_b32 s37, v255, 30
	v_readlane_b32 s38, v255, 31
	v_readlane_b32 s39, v255, 32
	v_readlane_b32 s40, v255, 33
	v_readlane_b32 s41, v255, 34
	v_readlane_b32 s42, v255, 35
	v_readlane_b32 s43, v255, 36
	v_readlane_b32 s44, v255, 37
	v_readlane_b32 s45, v255, 38
	v_readlane_b32 s46, v255, 39
	v_readlane_b32 s47, v255, 40
	v_readlane_b32 s50, v255, 43
	v_readlane_b32 s51, v255, 44
	s_ashr_i32 s6, s2, 31
	s_lshr_b32 s6, s6, 28
	s_add_i32 s6, s2, s6
	s_and_b32 s7, s6, 0x3fffff0
	s_sub_i32 s7, s2, s7
	s_lshl_b32 s6, s6, 2
	s_lshl_b32 s8, s7, 6
	s_andn2_b32 s6, s6, 63
	v_add_u32_e32 v30, s8, v2
	s_ashr_i32 s7, s6, 31
	v_ashrrev_i32_e32 v31, 31, v30
	v_lshl_add_u64 v[34:35], s[6:7], 2, v[0:1]
	v_add_u32_e32 v32, 32, v30
	v_lshlrev_b64 v[30:31], 12, v[30:31]
	v_ashrrev_i32_e32 v33, 31, v32
	v_lshl_add_u64 v[30:31], v[34:35], 0, v[30:31]
	v_lshlrev_b64 v[36:37], 12, v[32:33]
	global_load_dwordx4 v[30:33], v[30:31], off nt
	v_lshl_add_u64 v[34:35], v[34:35], 0, v[36:37]
	global_load_dwordx4 v[34:37], v[34:35], off nt
.LBB0_378:
	s_waitcnt vmcnt(0)
	v_mov_b32_e32 v6, v30
	v_mov_b32_e32 v7, v31
	v_mov_b32_e32 v8, v32
	v_mov_b32_e32 v9, v33
	v_mov_b32_e32 v10, v34
	v_mov_b32_e32 v11, v35
	v_mov_b32_e32 v12, v36
	v_mov_b32_e32 v13, v37
	v_add_u32_e32 v14, s6, v3
	v_add_u32_e32 v16, 0x2080, v4
	v_add_u32_e32 v17, 0x2088, v4
	v_add_u32_e32 v18, 0x400, v5
	v_ashrrev_i32_e32 v15, 31, v14
	v_lshlrev_b64 v[14:15], 11, v[14:15]
	s_ashr_i32 s9, s8, 31
	v_lshl_add_u64 v[14:15], s[4:5], 0, v[14:15]
	v_lshl_add_u64 v[14:15], s[8:9], 1, v[14:15]
	v_lshl_add_u64 v[14:15], v[14:15], 0, v[176:177]
	s_load_dword s6, s[88:89], 0x10
	s_load_dword s8, s[88:89], 0x0
	s_waitcnt lgkmcnt(0)
	s_lshr_b32 s6, s6, 16
	s_cmp_lg_u32 s6, 0
	s_cselect_b64 s[6:7], -1, 0
	s_cmp_lg_u64 s[6:7], 0
	s_addc_u32 s2, s8, s2
	s_cmpk_gt_i32 s2, 0xff
	s_cselect_b64 s[100:101], 0, -1
	s_cbranch_scc1 .Lcv_skip_378
	s_ashr_i32 s6, s2, 31
	s_lshr_b32 s6, s6, 28
	s_add_i32 s6, s2, s6
	s_and_b32 s7, s6, 0x3fffff0
	s_sub_i32 s7, s2, s7
	s_lshl_b32 s6, s6, 2
	s_lshl_b32 s8, s7, 6
	s_andn2_b32 s6, s6, 63
	v_add_u32_e32 v30, s8, v2
	s_ashr_i32 s7, s6, 31
	v_ashrrev_i32_e32 v31, 31, v30
	v_lshl_add_u64 v[34:35], s[6:7], 2, v[0:1]
	v_add_u32_e32 v32, 32, v30
	v_lshlrev_b64 v[30:31], 12, v[30:31]
	v_ashrrev_i32_e32 v33, 31, v32
	v_lshl_add_u64 v[30:31], v[34:35], 0, v[30:31]
	v_lshlrev_b64 v[36:37], 12, v[32:33]
	global_load_dwordx4 v[30:33], v[30:31], off nt
	v_lshl_add_u64 v[34:35], v[34:35], 0, v[36:37]
	global_load_dwordx4 v[34:37], v[34:35], off nt
